# plus: redundant post-barrier lgkmcnt waits removed from the K-loop MFMA segment heads
# speedup vs baseline: 1.0204x; 1.0031x over previous
; #define PG8_STAGE(bufoff, gbase, off, q) do { \
;         __builtin_amdgcn_global_load_lds((const unsigned*)((const char*)(gbase) + (off)), (LAS unsigned*)(lds + (bufoff) + ldsw), 16, 0, 0); \
;         __builtin_amdgcn_global_load_lds((const unsigned*)((const char*)(gbase) + (q) + (off)), (LAS unsigned*)(lds + (bufoff) + ldsw + 8192), 16, 0, 0); } while (0)
; #define PG8_LDA(dst, b, h) do { _Pragma("unroll") for (int m = 0; m < 4; ++m) _Pragma("unroll") for (int k = 0; k < 2; ++k) dst[m][k] = *(const LAS bf16x8*)(lds + PG8_SA(b, h) + aoff + m * 2048 + k * 1024); } while (0)
; #define PG8_LDB(dst, b, h) do { _Pragma("unroll") for (int n = 0; n < 2; ++n) _Pragma("unroll") for (int k = 0; k < 2; ++k) dst[n][k] = *(const LAS bf16x8*)(lds + PG8_SB(b, h) + boff + n * 2048 + k * 1024); } while (0)
; #define PG8_MMA(ai, bj, At, Bt) do { __builtin_amdgcn_s_setprio(1); _Pragma("unroll") for (int m = 0; m < 4; ++m) _Pragma("unroll") for (int n = 0; n < 2; ++n) _Pragma("unroll") for (int k = 0; k < 2; ++k) \
;         acc[ai][bj][m][n] = __builtin_amdgcn_mfma_f32_16x16x32_bf16(Bt[n][k], At[m][k], acc[ai][bj][m][n], 0, 0, 0); __builtin_amdgcn_s_setprio(0); } while (0)
; template <class Epi, class Sched>
; __device__ __forceinline__ void gemm_phase(LAS unsigned char* lds, const int tid, const Sched& S, const Epi& E) {
;     ...
;             const bool last = (t == nt - 2);
;             const char* a1 = cA + (size_t)(t + 1) * kstep;
;             const char* a2 = last ? nA : cA + (size_t)(t + 2) * kstep; const char* b2 = last ? nB : cB + (size_t)(t + 2) * kstep;
;             const char* a3 = a2 + kstep; const char* b3 = b2 + kstep;
;             const unsigned oA2 = last ? noffA : offA, oB2 = last ? noffB : offB;
;             const int qA2 = last ? nqA : qA, qB2 = last ? nqB : qB, hA2 = last ? nhA : hA, hB2 = last ? nhB : hB;
;             PG8_LDB(B0, 0, 0); PG8_LDB(B1, 0, 1); PG8_SCHED; PG8_LDA(At, 0, 0); PG8_STAGE(PG8_SA(1, 1), a1 + hA, offA, qA);
;             PG8_WAIT_V(8); PG8_WAIT_L(0); PG8_BAR; PG8_MMA(0, 0, At, B0); PG8_MMA(0, 1, At, B1); PG8_BAR; PG8_SCHED;
;             PG8_LDA(At, 0, 1); PG8_STAGE(PG8_SB(0, 0), b2, oB2, qB2); PG8_STAGE(PG8_SB(0, 1), b2 + hB2, oB2, qB2); PG8_STAGE(PG8_SA(0, 0), a2, oA2, qA2);
;             PG8_WAIT_V(8); PG8_WAIT_L(0); PG8_BAR; PG8_MMA(1, 0, At, B0); PG8_MMA(1, 1, At, B1); PG8_BAR; PG8_SCHED;
.LBB0_175:
	s_or_b32 vcc_lo, s17, 1
	s_mov_b32 vcc_hi, s21
	s_lshl_b64 s[10:11], vcc, 7
	s_add_u32 s17, s40, s6
	s_addc_u32 vcc_lo, s41, s7
	s_and_b64 s[6:7], exec, s[62:63]
	s_cselect_b32 vcc_hi, s82, vcc_lo
	s_cselect_b32 vcc_lo, s48, s17
	s_add_i32 s17, 0, 0x10000
	v_add_u32_e32 v133, s17, v147
	s_add_i32 s62, 0, 0x14000
	ds_read_b128 v[140:143], v133
	ds_read_b128 v[150:153], v133 offset:1024
	ds_read_b128 v[154:157], v133 offset:2048
	ds_read_b128 v[158:161], v133 offset:3072
	ds_read_b128 v[186:189], v133 offset:16384
	ds_read_b128 v[190:193], v133 offset:17408
	ds_read_b128 v[194:197], v133 offset:18432
	ds_read_b128 v[198:201], v133 offset:19456
	s_add_u32 s6, s68, s10
	s_addc_u32 s7, s16, s11
	s_add_i32 m0, s54, 0xc000
	ds_read_b128 v[202:205], v184
	ds_read_b128 v[206:209], v184 offset:1024
	ds_read_b128 v[210:213], v184 offset:2048
	ds_read_b128 v[214:217], v184 offset:3072
	ds_read_b128 v[218:221], v184 offset:4096
	ds_read_b128 v[222:225], v184 offset:5120
	ds_read_b128 v[226:229], v184 offset:6144
	ds_read_b128 v[230:233], v184 offset:7168
	global_load_lds_dwordx4 v134, s[6:7]
	s_add_u32 s6, s6, s66
	s_addc_u32 s7, s7, s67
	s_add_i32 m0, s54, 0xe000
	s_nop 0
	global_load_lds_dwordx4 v134, s[6:7]
	s_waitcnt vmcnt(8)
	s_waitcnt lgkmcnt(0)
	s_barrier
	s_setprio 1
	v_mfma_f32_16x16x32_bf16 v[126:129], v[140:143], v[202:205], v[126:129]
	v_mfma_f32_16x16x32_bf16 v[122:125], v[154:157], v[202:205], v[122:125]
	v_mfma_f32_16x16x32_bf16 v[110:113], v[140:143], v[210:213], v[110:113]
	v_mfma_f32_16x16x32_bf16 v[106:109], v[154:157], v[210:213], v[106:109]
	v_mfma_f32_16x16x32_bf16 v[94:97], v[140:143], v[218:221], v[94:97]
	v_mfma_f32_16x16x32_bf16 v[90:93], v[154:157], v[218:221], v[90:93]
	v_mfma_f32_16x16x32_bf16 v[78:81], v[140:143], v[226:229], v[78:81]
	v_mfma_f32_16x16x32_bf16 v[74:77], v[154:157], v[226:229], v[74:77]
	v_mfma_f32_16x16x32_bf16 v[126:129], v[150:153], v[206:209], v[126:129]
	v_mfma_f32_16x16x32_bf16 v[122:125], v[158:161], v[206:209], v[122:125]
	v_mfma_f32_16x16x32_bf16 v[110:113], v[150:153], v[214:217], v[110:113]
	v_mfma_f32_16x16x32_bf16 v[106:109], v[158:161], v[214:217], v[106:109]
	v_mfma_f32_16x16x32_bf16 v[94:97], v[150:153], v[222:225], v[94:97]
	v_mfma_f32_16x16x32_bf16 v[90:93], v[158:161], v[222:225], v[90:93]
	v_mfma_f32_16x16x32_bf16 v[78:81], v[150:153], v[230:233], v[78:81]
	v_mfma_f32_16x16x32_bf16 v[74:77], v[158:161], v[230:233], v[74:77]
	s_setprio 0
	s_setprio 1
	v_mfma_f32_16x16x32_bf16 v[118:121], v[186:189], v[202:205], v[118:121]
	v_mfma_f32_16x16x32_bf16 v[114:117], v[194:197], v[202:205], v[114:117]
	v_mfma_f32_16x16x32_bf16 v[102:105], v[186:189], v[210:213], v[102:105]
	v_mfma_f32_16x16x32_bf16 v[98:101], v[194:197], v[210:213], v[98:101]
	v_mfma_f32_16x16x32_bf16 v[86:89], v[186:189], v[218:221], v[86:89]
	v_mfma_f32_16x16x32_bf16 v[82:85], v[194:197], v[218:221], v[82:85]
	v_mfma_f32_16x16x32_bf16 v[70:73], v[186:189], v[226:229], v[70:73]
	v_mfma_f32_16x16x32_bf16 v[66:69], v[194:197], v[226:229], v[66:69]
	v_mfma_f32_16x16x32_bf16 v[118:121], v[190:193], v[206:209], v[118:121]
	v_mfma_f32_16x16x32_bf16 v[114:117], v[198:201], v[206:209], v[114:117]
	v_mfma_f32_16x16x32_bf16 v[102:105], v[190:193], v[214:217], v[102:105]
	v_mfma_f32_16x16x32_bf16 v[98:101], v[198:201], v[214:217], v[98:101]
	v_mfma_f32_16x16x32_bf16 v[86:89], v[190:193], v[222:225], v[86:89]
	v_mfma_f32_16x16x32_bf16 v[82:85], v[198:201], v[222:225], v[82:85]
	v_mfma_f32_16x16x32_bf16 v[70:73], v[190:193], v[230:233], v[70:73]
	v_mfma_f32_16x16x32_bf16 v[66:69], v[198:201], v[230:233], v[66:69]
	s_setprio 0
	s_barrier
	s_add_i32 s10, s17, s47
	s_ashr_i32 s11, s73, 31
	s_mov_b32 m0, s10
	s_add_u32 s6, s28, s73
	ds_read_b128 v[202:205], v184 offset:16384
	ds_read_b128 v[206:209], v184 offset:17408
	ds_read_b128 v[210:213], v184 offset:18432
	ds_read_b128 v[214:217], v184 offset:19456
	ds_read_b128 v[218:221], v184 offset:20480
	ds_read_b128 v[222:225], v184 offset:21504
	ds_read_b128 v[226:229], v184 offset:22528
	ds_read_b128 v[230:233], v184 offset:23552
	global_load_lds_dwordx4 v0, s[28:29]
	s_addc_u32 s7, s29, s11
	s_add_i32 m0, s10, 0x2000
	s_nop 0
	global_load_lds_dwordx4 v0, s[6:7]
	s_ashr_i32 s7, s19, 31
	s_add_u32 s6, s28, s19
	s_addc_u32 s7, s29, s7
	s_add_i32 s10, s62, s47
	s_mov_b32 m0, s10
	s_nop 0
	global_load_lds_dwordx4 v0, s[6:7]
	s_add_u32 s6, s6, s73
	s_addc_u32 s7, s7, s11
	s_add_i32 m0, s10, 0x2000
	s_nop 0
	global_load_lds_dwordx4 v0, s[6:7]
	s_add_u32 s6, vcc_lo, s64
	s_mov_b32 m0, s54
	s_addc_u32 s7, vcc_hi, s65
	global_load_lds_dwordx4 v136, vcc
	s_mov_b32 m0, s55
	s_nop 0
	global_load_lds_dwordx4 v136, s[6:7]
	s_waitcnt vmcnt(8)
	s_waitcnt lgkmcnt(0)
	s_barrier
; #define PG8_STAGE(bufoff, gbase, off, q) do { \
;         __builtin_amdgcn_global_load_lds((const unsigned*)((const char*)(gbase) + (off)), (LAS unsigned*)(lds + (bufoff) + ldsw), 16, 0, 0); \
;         __builtin_amdgcn_global_load_lds((const unsigned*)((const char*)(gbase) + (q) + (off)), (LAS unsigned*)(lds + (bufoff) + ldsw + 8192), 16, 0, 0); } while (0)
; #define PG8_LDA(dst, b, h) do { _Pragma("unroll") for (int m = 0; m < 4; ++m) _Pragma("unroll") for (int k = 0; k < 2; ++k) dst[m][k] = *(const LAS bf16x8*)(lds + PG8_SA(b, h) + aoff + m * 2048 + k * 1024); } while (0)
; #define PG8_LDB(dst, b, h) do { _Pragma("unroll") for (int n = 0; n < 2; ++n) _Pragma("unroll") for (int k = 0; k < 2; ++k) dst[n][k] = *(const LAS bf16x8*)(lds + PG8_SB(b, h) + boff + n * 2048 + k * 1024); } while (0)
; #define PG8_MMA(ai, bj, At, Bt) do { __builtin_amdgcn_s_setprio(1); _Pragma("unroll") for (int m = 0; m < 4; ++m) _Pragma("unroll") for (int n = 0; n < 2; ++n) _Pragma("unroll") for (int k = 0; k < 2; ++k) \
;         acc[ai][bj][m][n] = __builtin_amdgcn_mfma_f32_16x16x32_bf16(Bt[n][k], At[m][k], acc[ai][bj][m][n], 0, 0, 0); __builtin_amdgcn_s_setprio(0); } while (0)
; #define PG8_WAIT_V(n) asm volatile("s_waitcnt vmcnt(" #n ")" ::: "memory")
; #define PG8_WAIT_L(n) asm volatile("s_waitcnt lgkmcnt(" #n ")" ::: "memory")
; #define PG8_BAR __builtin_amdgcn_s_barrier()
; #define PG8_SCHED __builtin_amdgcn_sched_barrier(0)
; template <class Epi, class Sched>
; __device__ __forceinline__ void gemm_phase(LAS unsigned char* lds, const int tid, const Sched& S, const Epi& E) {
;     ...
;             PG8_WAIT_V(8); PG8_WAIT_L(0); PG8_BAR; PG8_MMA(1, 0, At, B0); PG8_MMA(1, 1, At, B1); PG8_BAR; PG8_SCHED;
;             PG8_LDB(B0, 1, 0); PG8_LDB(B1, 1, 1); PG8_SCHED; PG8_LDA(At, 1, 0); PG8_STAGE(PG8_SA(0, 1), a2 + hA2, oA2, qA2);
;             PG8_WAIT_V(8); PG8_WAIT_L(0); PG8_BAR; PG8_MMA(0, 0, At, B0); PG8_MMA(0, 1, At, B1); PG8_BAR; PG8_SCHED;
	s_setprio 1
	v_mfma_f32_16x16x32_bf16 v[62:65], v[140:143], v[202:205], v[62:65]
	v_mfma_f32_16x16x32_bf16 v[58:61], v[154:157], v[202:205], v[58:61]
	v_mfma_f32_16x16x32_bf16 v[46:49], v[140:143], v[210:213], v[46:49]
	v_mfma_f32_16x16x32_bf16 v[42:45], v[154:157], v[210:213], v[42:45]
	v_mfma_f32_16x16x32_bf16 v[30:33], v[140:143], v[218:221], v[30:33]
	v_mfma_f32_16x16x32_bf16 v[26:29], v[154:157], v[218:221], v[26:29]
	v_mfma_f32_16x16x32_bf16 v[14:17], v[140:143], v[226:229], v[14:17]
	v_mfma_f32_16x16x32_bf16 v[10:13], v[154:157], v[226:229], v[10:13]
	v_mfma_f32_16x16x32_bf16 v[62:65], v[150:153], v[206:209], v[62:65]
	v_mfma_f32_16x16x32_bf16 v[58:61], v[158:161], v[206:209], v[58:61]
	v_mfma_f32_16x16x32_bf16 v[46:49], v[150:153], v[214:217], v[46:49]
	v_mfma_f32_16x16x32_bf16 v[42:45], v[158:161], v[214:217], v[42:45]
	v_mfma_f32_16x16x32_bf16 v[30:33], v[150:153], v[222:225], v[30:33]
	v_mfma_f32_16x16x32_bf16 v[26:29], v[158:161], v[222:225], v[26:29]
	v_mfma_f32_16x16x32_bf16 v[14:17], v[150:153], v[230:233], v[14:17]
	v_mfma_f32_16x16x32_bf16 v[10:13], v[158:161], v[230:233], v[10:13]
	s_setprio 0
	s_setprio 1
	v_mfma_f32_16x16x32_bf16 v[54:57], v[186:189], v[202:205], v[54:57]
	v_mfma_f32_16x16x32_bf16 v[50:53], v[194:197], v[202:205], v[50:53]
	v_mfma_f32_16x16x32_bf16 v[38:41], v[186:189], v[210:213], v[38:41]
	v_mfma_f32_16x16x32_bf16 v[34:37], v[194:197], v[210:213], v[34:37]
	v_mfma_f32_16x16x32_bf16 v[22:25], v[186:189], v[218:221], v[22:25]
	v_mfma_f32_16x16x32_bf16 v[18:21], v[194:197], v[218:221], v[18:21]
	v_mfma_f32_16x16x32_bf16 v[6:9], v[186:189], v[226:229], v[6:9]
	v_mfma_f32_16x16x32_bf16 v[2:5], v[194:197], v[226:229], v[2:5]
	v_mfma_f32_16x16x32_bf16 v[54:57], v[190:193], v[206:209], v[54:57]
	v_mfma_f32_16x16x32_bf16 v[50:53], v[198:201], v[206:209], v[50:53]
	v_mfma_f32_16x16x32_bf16 v[38:41], v[190:193], v[214:217], v[38:41]
	v_mfma_f32_16x16x32_bf16 v[34:37], v[198:201], v[214:217], v[34:37]
	v_mfma_f32_16x16x32_bf16 v[22:25], v[190:193], v[222:225], v[22:25]
	v_mfma_f32_16x16x32_bf16 v[18:21], v[198:201], v[222:225], v[18:21]
	v_mfma_f32_16x16x32_bf16 v[6:9], v[190:193], v[230:233], v[6:9]
	v_mfma_f32_16x16x32_bf16 v[2:5], v[198:201], v[230:233], v[2:5]
	s_setprio 0
	s_barrier
	s_add_i32 s10, 0, 0x18000
	s_add_i32 s11, 0, 0x1c000
	ds_read_b128 v[140:143], v133 offset:32768
	ds_read_b128 v[150:153], v133 offset:33792
	ds_read_b128 v[154:157], v133 offset:34816
	ds_read_b128 v[158:161], v133 offset:35840
	ds_read_b128 v[186:189], v133 offset:49152
	ds_read_b128 v[190:193], v133 offset:50176
	ds_read_b128 v[194:197], v133 offset:51200
	ds_read_b128 v[198:201], v133 offset:52224
	s_add_u32 s6, vcc_lo, s58
	s_addc_u32 s7, vcc_hi, s59
	s_mov_b32 m0, s91
	ds_read_b128 v[202:205], v184 offset:32768
	ds_read_b128 v[206:209], v184 offset:33792
	ds_read_b128 v[210:213], v184 offset:34816
	ds_read_b128 v[214:217], v184 offset:35840
	ds_read_b128 v[218:221], v184 offset:36864
	ds_read_b128 v[222:225], v184 offset:37888
	ds_read_b128 v[226:229], v184 offset:38912
	ds_read_b128 v[230:233], v184 offset:39936
	global_load_lds_dwordx4 v136, s[6:7]
	s_add_u32 s6, s6, s64
	s_addc_u32 s7, s7, s65
	s_mov_b32 m0, s93
	s_nop 0
	global_load_lds_dwordx4 v136, s[6:7]
	s_waitcnt vmcnt(8)
	s_waitcnt lgkmcnt(0)
	s_barrier
	s_setprio 1
	v_mfma_f32_16x16x32_bf16 v[126:129], v[140:143], v[202:205], v[126:129]
	v_mfma_f32_16x16x32_bf16 v[122:125], v[154:157], v[202:205], v[122:125]
	v_mfma_f32_16x16x32_bf16 v[110:113], v[140:143], v[210:213], v[110:113]
	v_mfma_f32_16x16x32_bf16 v[106:109], v[154:157], v[210:213], v[106:109]
	v_mfma_f32_16x16x32_bf16 v[94:97], v[140:143], v[218:221], v[94:97]
	v_mfma_f32_16x16x32_bf16 v[90:93], v[154:157], v[218:221], v[90:93]
	v_mfma_f32_16x16x32_bf16 v[78:81], v[140:143], v[226:229], v[78:81]
	v_mfma_f32_16x16x32_bf16 v[74:77], v[154:157], v[226:229], v[74:77]
	v_mfma_f32_16x16x32_bf16 v[126:129], v[150:153], v[206:209], v[126:129]
	v_mfma_f32_16x16x32_bf16 v[122:125], v[158:161], v[206:209], v[122:125]
	v_mfma_f32_16x16x32_bf16 v[110:113], v[150:153], v[214:217], v[110:113]
	v_mfma_f32_16x16x32_bf16 v[106:109], v[158:161], v[214:217], v[106:109]
	v_mfma_f32_16x16x32_bf16 v[94:97], v[150:153], v[222:225], v[94:97]
	v_mfma_f32_16x16x32_bf16 v[90:93], v[158:161], v[222:225], v[90:93]
	v_mfma_f32_16x16x32_bf16 v[78:81], v[150:153], v[230:233], v[78:81]
	v_mfma_f32_16x16x32_bf16 v[74:77], v[158:161], v[230:233], v[74:77]
	s_setprio 0
	s_setprio 1
	v_mfma_f32_16x16x32_bf16 v[118:121], v[186:189], v[202:205], v[118:121]
	v_mfma_f32_16x16x32_bf16 v[114:117], v[194:197], v[202:205], v[114:117]
	v_mfma_f32_16x16x32_bf16 v[102:105], v[186:189], v[210:213], v[102:105]
	v_mfma_f32_16x16x32_bf16 v[98:101], v[194:197], v[210:213], v[98:101]
	v_mfma_f32_16x16x32_bf16 v[86:89], v[186:189], v[218:221], v[86:89]
	v_mfma_f32_16x16x32_bf16 v[82:85], v[194:197], v[218:221], v[82:85]
	v_mfma_f32_16x16x32_bf16 v[70:73], v[186:189], v[226:229], v[70:73]
	v_mfma_f32_16x16x32_bf16 v[66:69], v[194:197], v[226:229], v[66:69]
	v_mfma_f32_16x16x32_bf16 v[118:121], v[190:193], v[206:209], v[118:121]
	v_mfma_f32_16x16x32_bf16 v[114:117], v[198:201], v[206:209], v[114:117]
	v_mfma_f32_16x16x32_bf16 v[102:105], v[190:193], v[214:217], v[102:105]
	v_mfma_f32_16x16x32_bf16 v[98:101], v[198:201], v[214:217], v[98:101]
	v_mfma_f32_16x16x32_bf16 v[86:89], v[190:193], v[222:225], v[86:89]
	v_mfma_f32_16x16x32_bf16 v[82:85], v[198:201], v[222:225], v[82:85]
	v_mfma_f32_16x16x32_bf16 v[70:73], v[190:193], v[230:233], v[70:73]
	v_mfma_f32_16x16x32_bf16 v[66:69], v[198:201], v[230:233], v[66:69]
	s_setprio 0
	s_barrier
; #define PG8_STAGE(bufoff, gbase, off, q) do { \
;         __builtin_amdgcn_global_load_lds((const unsigned*)((const char*)(gbase) + (off)), (LAS unsigned*)(lds + (bufoff) + ldsw), 16, 0, 0); \
;         __builtin_amdgcn_global_load_lds((const unsigned*)((const char*)(gbase) + (q) + (off)), (LAS unsigned*)(lds + (bufoff) + ldsw + 8192), 16, 0, 0); } while (0)
; #define PG8_LDA(dst, b, h) do { _Pragma("unroll") for (int m = 0; m < 4; ++m) _Pragma("unroll") for (int k = 0; k < 2; ++k) dst[m][k] = *(const LAS bf16x8*)(lds + PG8_SA(b, h) + aoff + m * 2048 + k * 1024); } while (0)
; #define PG8_MMA(ai, bj, At, Bt) do { __builtin_amdgcn_s_setprio(1); _Pragma("unroll") for (int m = 0; m < 4; ++m) _Pragma("unroll") for (int n = 0; n < 2; ++n) _Pragma("unroll") for (int k = 0; k < 2; ++k) \
;         acc[ai][bj][m][n] = __builtin_amdgcn_mfma_f32_16x16x32_bf16(Bt[n][k], At[m][k], acc[ai][bj][m][n], 0, 0, 0); __builtin_amdgcn_s_setprio(0); } while (0)
; #define PG8_WAIT_V(n) asm volatile("s_waitcnt vmcnt(" #n ")" ::: "memory")
; #define PG8_WAIT_L(n) asm volatile("s_waitcnt lgkmcnt(" #n ")" ::: "memory")
; #define PG8_BAR __builtin_amdgcn_s_barrier()
; #define PG8_SCHED __builtin_amdgcn_sched_barrier(0)
; template <class Epi, class Sched>
; __device__ __forceinline__ void gemm_phase(LAS unsigned char* lds, const int tid, const Sched& S, const Epi& E) {
;     ...
;             PG8_LDA(At, 1, 1); PG8_STAGE(PG8_SB(1, 0), b3, oB2, qB2); PG8_STAGE(PG8_SB(1, 1), b3 + hB2, oB2, qB2); PG8_STAGE(PG8_SA(1, 0), a3, oA2, qA2);
;             PG8_WAIT_V(8); PG8_WAIT_L(0); PG8_BAR; PG8_MMA(1, 0, At, B0); PG8_MMA(1, 1, At, B1); PG8_BAR; PG8_SCHED;
;         }
	s_add_i32 s6, s10, s47
	s_add_i32 m0, s6, 0xffffff80
	ds_read_b128 v[202:205], v184 offset:49152
	ds_read_b128 v[206:209], v184 offset:50176
	ds_read_b128 v[210:213], v184 offset:51200
	ds_read_b128 v[214:217], v184 offset:52224
	ds_read_b128 v[218:221], v184 offset:53248
	ds_read_b128 v[222:225], v184 offset:54272
	ds_read_b128 v[226:229], v184 offset:55296
	ds_read_b128 v[230:233], v184 offset:56320
	global_load_lds_dwordx4 v0, s[28:29] offset:128
	s_add_i32 m0, s6, 0x1f80
	s_add_i32 s6, s11, s47
	s_ashr_i32 s100, s73, 31
	s_add_u32 s98, s28, s73
	s_addc_u32 s99, s29, s100
	global_load_lds_dwordx4 v0, s[98:99] offset:128
	s_add_i32 m0, s6, 0xffffff80
	s_nop 0
	s_ashr_i32 s101, s19, 31
	s_add_u32 s98, s28, s19
	s_addc_u32 s99, s29, s101
	global_load_lds_dwordx4 v0, s[98:99] offset:128
	s_add_i32 m0, s6, 0x1f80
	s_nop 0
	s_add_u32 s98, s98, s73
	s_addc_u32 s99, s99, s100
	global_load_lds_dwordx4 v0, s[98:99] offset:128
	s_add_i32 m0, s77, 0xffffff80
	s_nop 0
	global_load_lds_dwordx4 v136, vcc offset:128
	s_add_i32 m0, s88, 0xffffff80
	s_nop 0
	s_add_u32 s98, vcc_lo, s64
	s_addc_u32 s99, vcc_hi, s65
	global_load_lds_dwordx4 v136, s[98:99] offset:128
	s_waitcnt vmcnt(8)
	s_waitcnt lgkmcnt(0)
	s_barrier
	s_setprio 1
	v_mfma_f32_16x16x32_bf16 v[62:65], v[140:143], v[202:205], v[62:65]
	v_mfma_f32_16x16x32_bf16 v[58:61], v[154:157], v[202:205], v[58:61]
	v_mfma_f32_16x16x32_bf16 v[46:49], v[140:143], v[210:213], v[46:49]
	v_mfma_f32_16x16x32_bf16 v[42:45], v[154:157], v[210:213], v[42:45]
	v_mfma_f32_16x16x32_bf16 v[30:33], v[140:143], v[218:221], v[30:33]
	v_mfma_f32_16x16x32_bf16 v[26:29], v[154:157], v[218:221], v[26:29]
	v_mfma_f32_16x16x32_bf16 v[14:17], v[140:143], v[226:229], v[14:17]
	v_mfma_f32_16x16x32_bf16 v[10:13], v[154:157], v[226:229], v[10:13]
	v_mfma_f32_16x16x32_bf16 v[62:65], v[150:153], v[206:209], v[62:65]
	v_mfma_f32_16x16x32_bf16 v[58:61], v[158:161], v[206:209], v[58:61]
	v_mfma_f32_16x16x32_bf16 v[46:49], v[150:153], v[214:217], v[46:49]
	v_mfma_f32_16x16x32_bf16 v[42:45], v[158:161], v[214:217], v[42:45]
	v_mfma_f32_16x16x32_bf16 v[30:33], v[150:153], v[222:225], v[30:33]
	v_mfma_f32_16x16x32_bf16 v[26:29], v[158:161], v[222:225], v[26:29]
	v_mfma_f32_16x16x32_bf16 v[14:17], v[150:153], v[230:233], v[14:17]
	v_mfma_f32_16x16x32_bf16 v[10:13], v[158:161], v[230:233], v[10:13]
	s_setprio 0
	s_setprio 1
	v_mfma_f32_16x16x32_bf16 v[54:57], v[186:189], v[202:205], v[54:57]
	v_mfma_f32_16x16x32_bf16 v[50:53], v[194:197], v[202:205], v[50:53]
	v_mfma_f32_16x16x32_bf16 v[38:41], v[186:189], v[210:213], v[38:41]
	v_mfma_f32_16x16x32_bf16 v[34:37], v[194:197], v[210:213], v[34:37]
	v_mfma_f32_16x16x32_bf16 v[22:25], v[186:189], v[218:221], v[22:25]
	v_mfma_f32_16x16x32_bf16 v[18:21], v[194:197], v[218:221], v[18:21]
	v_mfma_f32_16x16x32_bf16 v[6:9], v[186:189], v[226:229], v[6:9]
	v_mfma_f32_16x16x32_bf16 v[2:5], v[194:197], v[226:229], v[2:5]
	v_mfma_f32_16x16x32_bf16 v[54:57], v[190:193], v[206:209], v[54:57]
	v_mfma_f32_16x16x32_bf16 v[50:53], v[198:201], v[206:209], v[50:53]
	v_mfma_f32_16x16x32_bf16 v[38:41], v[190:193], v[214:217], v[38:41]
	v_mfma_f32_16x16x32_bf16 v[34:37], v[198:201], v[214:217], v[34:37]
	v_mfma_f32_16x16x32_bf16 v[22:25], v[190:193], v[222:225], v[22:25]
	v_mfma_f32_16x16x32_bf16 v[18:21], v[198:201], v[222:225], v[18:21]
	v_mfma_f32_16x16x32_bf16 v[6:9], v[190:193], v[230:233], v[6:9]
	v_mfma_f32_16x16x32_bf16 v[2:5], v[198:201], v[230:233], v[2:5]
	s_setprio 0
	s_barrier
	s_cmp_ge_i32 s20, s37
	s_cbranch_scc1 .LBB0_177
	s_mov_b32 s17, s20
	s_branch .LBB0_173

; #define PG8_STAGE(bufoff, gbase, off, q) do { \
;         __builtin_amdgcn_global_load_lds((const unsigned*)((const char*)(gbase) + (off)), (LAS unsigned*)(lds + (bufoff) + ldsw), 16, 0, 0); \
;         __builtin_amdgcn_global_load_lds((const unsigned*)((const char*)(gbase) + (q) + (off)), (LAS unsigned*)(lds + (bufoff) + ldsw + 8192), 16, 0, 0); } while (0)
; #define PG8_LDA(dst, b, h) do { _Pragma("unroll") for (int m = 0; m < 4; ++m) _Pragma("unroll") for (int k = 0; k < 2; ++k) dst[m][k] = *(const LAS bf16x8*)(lds + PG8_SA(b, h) + aoff + m * 2048 + k * 1024); } while (0)
; #define PG8_LDB(dst, b, h) do { _Pragma("unroll") for (int n = 0; n < 2; ++n) _Pragma("unroll") for (int k = 0; k < 2; ++k) dst[n][k] = *(const LAS bf16x8*)(lds + PG8_SB(b, h) + boff + n * 2048 + k * 1024); } while (0)
; #define PG8_MMA(ai, bj, At, Bt) do { __builtin_amdgcn_s_setprio(1); _Pragma("unroll") for (int m = 0; m < 4; ++m) _Pragma("unroll") for (int n = 0; n < 2; ++n) _Pragma("unroll") for (int k = 0; k < 2; ++k) \
;         acc[ai][bj][m][n] = __builtin_amdgcn_mfma_f32_16x16x32_bf16(Bt[n][k], At[m][k], acc[ai][bj][m][n], 0, 0, 0); __builtin_amdgcn_s_setprio(0); } while (0)
; template <class Epi, class Sched>
; __device__ __forceinline__ void gemm_phase(LAS unsigned char* lds, const int tid, const Sched& S, const Epi& E) {
;     ...
;             const bool last = (t == nt - 2);
;             const char* a1 = cA + (size_t)(t + 1) * kstep;
;             const char* a2 = last ? nA : cA + (size_t)(t + 2) * kstep; const char* b2 = last ? nB : cB + (size_t)(t + 2) * kstep;
;             const char* a3 = a2 + kstep; const char* b3 = b2 + kstep;
;             const unsigned oA2 = last ? noffA : offA, oB2 = last ? noffB : offB;
;             const int qA2 = last ? nqA : qA, qB2 = last ? nqB : qB, hA2 = last ? nhA : hA, hB2 = last ? nhB : hB;
;             PG8_LDB(B0, 0, 0); PG8_LDB(B1, 0, 1); PG8_SCHED; PG8_LDA(At, 0, 0); PG8_STAGE(PG8_SA(1, 1), a1 + hA, offA, qA);
;             PG8_WAIT_V(8); PG8_WAIT_L(0); PG8_BAR; PG8_MMA(0, 0, At, B0); PG8_MMA(0, 1, At, B1); PG8_BAR; PG8_SCHED;
;             PG8_LDA(At, 0, 1); PG8_STAGE(PG8_SB(0, 0), b2, oB2, qB2); PG8_STAGE(PG8_SB(0, 1), b2 + hB2, oB2, qB2); PG8_STAGE(PG8_SA(0, 0), a2, oA2, qA2);
;             PG8_WAIT_V(8); PG8_WAIT_L(0); PG8_BAR; PG8_MMA(1, 0, At, B0); PG8_MMA(1, 1, At, B1); PG8_BAR; PG8_SCHED;
.Lk0a_175:
	s_or_b32 vcc_lo, s17, 1
	s_mov_b32 vcc_hi, s21
	s_lshl_b64 s[10:11], vcc, 7
	s_add_u32 s17, s40, s6
	s_addc_u32 vcc_lo, s41, s7
	s_and_b64 s[6:7], exec, s[62:63]
	s_cselect_b32 vcc_hi, s82, vcc_lo
	s_cselect_b32 vcc_lo, s48, s17
	s_add_i32 s17, 0, 0x10000
	v_add_u32_e32 v133, s17, v147
	s_add_i32 s62, 0, 0x14000
	ds_read_b128 v[140:143], v133
	ds_read_b128 v[150:153], v133 offset:1024
	ds_read_b128 v[154:157], v133 offset:2048
	ds_read_b128 v[158:161], v133 offset:3072
	ds_read_b128 v[186:189], v133 offset:16384
	ds_read_b128 v[190:193], v133 offset:17408
	ds_read_b128 v[194:197], v133 offset:18432
	ds_read_b128 v[198:201], v133 offset:19456
	s_add_u32 s6, s68, s10
	s_addc_u32 s7, s16, s11
	s_add_i32 m0, s54, 0xc000
	ds_read_b128 v[202:205], v184
	ds_read_b128 v[206:209], v184 offset:1024
	ds_read_b128 v[210:213], v184 offset:2048
	ds_read_b128 v[214:217], v184 offset:3072
	ds_read_b128 v[218:221], v184 offset:4096
	ds_read_b128 v[222:225], v184 offset:5120
	ds_read_b128 v[226:229], v184 offset:6144
	ds_read_b128 v[230:233], v184 offset:7168
	global_load_lds_dwordx4 v134, s[6:7]
	s_add_u32 s6, s6, s66
	s_addc_u32 s7, s7, s67
	s_add_i32 m0, s54, 0xe000
	s_nop 0
	global_load_lds_dwordx4 v134, s[6:7]
	s_waitcnt vmcnt(16)
	s_waitcnt lgkmcnt(0)
	s_barrier
	s_setprio 1
	v_mfma_f32_16x16x32_bf16 v[126:129], v[140:143], v[202:205], v[126:129]
	v_mfma_f32_16x16x32_bf16 v[122:125], v[154:157], v[202:205], v[122:125]
	v_mfma_f32_16x16x32_bf16 v[110:113], v[140:143], v[210:213], v[110:113]
	v_mfma_f32_16x16x32_bf16 v[106:109], v[154:157], v[210:213], v[106:109]
	v_mfma_f32_16x16x32_bf16 v[94:97], v[140:143], v[218:221], v[94:97]
	v_mfma_f32_16x16x32_bf16 v[90:93], v[154:157], v[218:221], v[90:93]
	v_mfma_f32_16x16x32_bf16 v[78:81], v[140:143], v[226:229], v[78:81]
	v_mfma_f32_16x16x32_bf16 v[74:77], v[154:157], v[226:229], v[74:77]
	v_mfma_f32_16x16x32_bf16 v[126:129], v[150:153], v[206:209], v[126:129]
	v_mfma_f32_16x16x32_bf16 v[122:125], v[158:161], v[206:209], v[122:125]
	v_mfma_f32_16x16x32_bf16 v[110:113], v[150:153], v[214:217], v[110:113]
	v_mfma_f32_16x16x32_bf16 v[106:109], v[158:161], v[214:217], v[106:109]
	v_mfma_f32_16x16x32_bf16 v[94:97], v[150:153], v[222:225], v[94:97]
	v_mfma_f32_16x16x32_bf16 v[90:93], v[158:161], v[222:225], v[90:93]
	v_mfma_f32_16x16x32_bf16 v[78:81], v[150:153], v[230:233], v[78:81]
	v_mfma_f32_16x16x32_bf16 v[74:77], v[158:161], v[230:233], v[74:77]
	s_setprio 0
	s_setprio 1
	v_mfma_f32_16x16x32_bf16 v[118:121], v[186:189], v[202:205], v[118:121]
	v_mfma_f32_16x16x32_bf16 v[114:117], v[194:197], v[202:205], v[114:117]
	v_mfma_f32_16x16x32_bf16 v[102:105], v[186:189], v[210:213], v[102:105]
	v_mfma_f32_16x16x32_bf16 v[98:101], v[194:197], v[210:213], v[98:101]
	v_mfma_f32_16x16x32_bf16 v[86:89], v[186:189], v[218:221], v[86:89]
	v_mfma_f32_16x16x32_bf16 v[82:85], v[194:197], v[218:221], v[82:85]
	v_mfma_f32_16x16x32_bf16 v[70:73], v[186:189], v[226:229], v[70:73]
	v_mfma_f32_16x16x32_bf16 v[66:69], v[194:197], v[226:229], v[66:69]
	v_mfma_f32_16x16x32_bf16 v[118:121], v[190:193], v[206:209], v[118:121]
	v_mfma_f32_16x16x32_bf16 v[114:117], v[198:201], v[206:209], v[114:117]
	v_mfma_f32_16x16x32_bf16 v[102:105], v[190:193], v[214:217], v[102:105]
	v_mfma_f32_16x16x32_bf16 v[98:101], v[198:201], v[214:217], v[98:101]
	v_mfma_f32_16x16x32_bf16 v[86:89], v[190:193], v[222:225], v[86:89]
	v_mfma_f32_16x16x32_bf16 v[82:85], v[198:201], v[222:225], v[82:85]
	v_mfma_f32_16x16x32_bf16 v[70:73], v[190:193], v[230:233], v[70:73]
	v_mfma_f32_16x16x32_bf16 v[66:69], v[198:201], v[230:233], v[66:69]
	s_setprio 0
	s_barrier
	s_add_i32 s10, s17, s47
	s_ashr_i32 s11, s73, 31
	s_mov_b32 m0, s10
	s_add_u32 s6, s28, s73
	ds_read_b128 v[202:205], v184 offset:16384
	ds_read_b128 v[206:209], v184 offset:17408
	ds_read_b128 v[210:213], v184 offset:18432
	ds_read_b128 v[214:217], v184 offset:19456
	ds_read_b128 v[218:221], v184 offset:20480
	ds_read_b128 v[222:225], v184 offset:21504
	ds_read_b128 v[226:229], v184 offset:22528
	ds_read_b128 v[230:233], v184 offset:23552
	global_load_lds_dwordx4 v0, s[28:29]
	s_addc_u32 s7, s29, s11
	s_add_i32 m0, s10, 0x2000
	s_nop 0
	global_load_lds_dwordx4 v0, s[6:7]
	s_ashr_i32 s7, s19, 31
	s_add_u32 s6, s28, s19
	s_addc_u32 s7, s29, s7
	s_add_i32 s10, s62, s47
	s_mov_b32 m0, s10
	s_nop 0
	global_load_lds_dwordx4 v0, s[6:7]
	s_add_u32 s6, s6, s73
	s_addc_u32 s7, s7, s11
	s_add_i32 m0, s10, 0x2000
	s_nop 0
	global_load_lds_dwordx4 v0, s[6:7]
	s_add_u32 s6, vcc_lo, s64
	s_mov_b32 m0, s54
	s_addc_u32 s7, vcc_hi, s65
	global_load_lds_dwordx4 v136, vcc
	s_mov_b32 m0, s55
	s_nop 0
	global_load_lds_dwordx4 v136, s[6:7]
	s_waitcnt vmcnt(16)
	s_waitcnt lgkmcnt(0)
	s_barrier
; #define PG8_STAGE(bufoff, gbase, off, q) do { \
;         __builtin_amdgcn_global_load_lds((const unsigned*)((const char*)(gbase) + (off)), (LAS unsigned*)(lds + (bufoff) + ldsw), 16, 0, 0); \
;         __builtin_amdgcn_global_load_lds((const unsigned*)((const char*)(gbase) + (q) + (off)), (LAS unsigned*)(lds + (bufoff) + ldsw + 8192), 16, 0, 0); } while (0)
; #define PG8_LDA(dst, b, h) do { _Pragma("unroll") for (int m = 0; m < 4; ++m) _Pragma("unroll") for (int k = 0; k < 2; ++k) dst[m][k] = *(const LAS bf16x8*)(lds + PG8_SA(b, h) + aoff + m * 2048 + k * 1024); } while (0)
; #define PG8_LDB(dst, b, h) do { _Pragma("unroll") for (int n = 0; n < 2; ++n) _Pragma("unroll") for (int k = 0; k < 2; ++k) dst[n][k] = *(const LAS bf16x8*)(lds + PG8_SB(b, h) + boff + n * 2048 + k * 1024); } while (0)
; #define PG8_MMA(ai, bj, At, Bt) do { __builtin_amdgcn_s_setprio(1); _Pragma("unroll") for (int m = 0; m < 4; ++m) _Pragma("unroll") for (int n = 0; n < 2; ++n) _Pragma("unroll") for (int k = 0; k < 2; ++k) \
;         acc[ai][bj][m][n] = __builtin_amdgcn_mfma_f32_16x16x32_bf16(Bt[n][k], At[m][k], acc[ai][bj][m][n], 0, 0, 0); __builtin_amdgcn_s_setprio(0); } while (0)
; #define PG8_WAIT_V(n) asm volatile("s_waitcnt vmcnt(" #n ")" ::: "memory")
; #define PG8_WAIT_L(n) asm volatile("s_waitcnt lgkmcnt(" #n ")" ::: "memory")
; #define PG8_BAR __builtin_amdgcn_s_barrier()
; #define PG8_SCHED __builtin_amdgcn_sched_barrier(0)
; template <class Epi, class Sched>
; __device__ __forceinline__ void gemm_phase(LAS unsigned char* lds, const int tid, const Sched& S, const Epi& E) {
;     ...
;             PG8_WAIT_V(8); PG8_WAIT_L(0); PG8_BAR; PG8_MMA(1, 0, At, B0); PG8_MMA(1, 1, At, B1); PG8_BAR; PG8_SCHED;
;             PG8_LDB(B0, 1, 0); PG8_LDB(B1, 1, 1); PG8_SCHED; PG8_LDA(At, 1, 0); PG8_STAGE(PG8_SA(0, 1), a2 + hA2, oA2, qA2);
;             PG8_WAIT_V(8); PG8_WAIT_L(0); PG8_BAR; PG8_MMA(0, 0, At, B0); PG8_MMA(0, 1, At, B1); PG8_BAR; PG8_SCHED;
	s_setprio 1
	v_mfma_f32_16x16x32_bf16 v[62:65], v[140:143], v[202:205], v[62:65]
	v_mfma_f32_16x16x32_bf16 v[58:61], v[154:157], v[202:205], v[58:61]
	v_mfma_f32_16x16x32_bf16 v[46:49], v[140:143], v[210:213], v[46:49]
	v_mfma_f32_16x16x32_bf16 v[42:45], v[154:157], v[210:213], v[42:45]
	v_mfma_f32_16x16x32_bf16 v[30:33], v[140:143], v[218:221], v[30:33]
	v_mfma_f32_16x16x32_bf16 v[26:29], v[154:157], v[218:221], v[26:29]
	v_mfma_f32_16x16x32_bf16 v[14:17], v[140:143], v[226:229], v[14:17]
	v_mfma_f32_16x16x32_bf16 v[10:13], v[154:157], v[226:229], v[10:13]
	v_mfma_f32_16x16x32_bf16 v[62:65], v[150:153], v[206:209], v[62:65]
	v_mfma_f32_16x16x32_bf16 v[58:61], v[158:161], v[206:209], v[58:61]
	v_mfma_f32_16x16x32_bf16 v[46:49], v[150:153], v[214:217], v[46:49]
	v_mfma_f32_16x16x32_bf16 v[42:45], v[158:161], v[214:217], v[42:45]
	v_mfma_f32_16x16x32_bf16 v[30:33], v[150:153], v[222:225], v[30:33]
	v_mfma_f32_16x16x32_bf16 v[26:29], v[158:161], v[222:225], v[26:29]
	v_mfma_f32_16x16x32_bf16 v[14:17], v[150:153], v[230:233], v[14:17]
	v_mfma_f32_16x16x32_bf16 v[10:13], v[158:161], v[230:233], v[10:13]
	s_setprio 0
	s_setprio 1
	v_mfma_f32_16x16x32_bf16 v[54:57], v[186:189], v[202:205], v[54:57]
	v_mfma_f32_16x16x32_bf16 v[50:53], v[194:197], v[202:205], v[50:53]
	v_mfma_f32_16x16x32_bf16 v[38:41], v[186:189], v[210:213], v[38:41]
	v_mfma_f32_16x16x32_bf16 v[34:37], v[194:197], v[210:213], v[34:37]
	v_mfma_f32_16x16x32_bf16 v[22:25], v[186:189], v[218:221], v[22:25]
	v_mfma_f32_16x16x32_bf16 v[18:21], v[194:197], v[218:221], v[18:21]
	v_mfma_f32_16x16x32_bf16 v[6:9], v[186:189], v[226:229], v[6:9]
	v_mfma_f32_16x16x32_bf16 v[2:5], v[194:197], v[226:229], v[2:5]
	v_mfma_f32_16x16x32_bf16 v[54:57], v[190:193], v[206:209], v[54:57]
	v_mfma_f32_16x16x32_bf16 v[50:53], v[198:201], v[206:209], v[50:53]
	v_mfma_f32_16x16x32_bf16 v[38:41], v[190:193], v[214:217], v[38:41]
	v_mfma_f32_16x16x32_bf16 v[34:37], v[198:201], v[214:217], v[34:37]
	v_mfma_f32_16x16x32_bf16 v[22:25], v[190:193], v[222:225], v[22:25]
	v_mfma_f32_16x16x32_bf16 v[18:21], v[198:201], v[222:225], v[18:21]
	v_mfma_f32_16x16x32_bf16 v[6:9], v[190:193], v[230:233], v[6:9]
	v_mfma_f32_16x16x32_bf16 v[2:5], v[198:201], v[230:233], v[2:5]
	s_setprio 0
	s_barrier
	s_add_i32 s10, 0, 0x18000
	s_add_i32 s11, 0, 0x1c000
	ds_read_b128 v[140:143], v133 offset:32768
	ds_read_b128 v[150:153], v133 offset:33792
	ds_read_b128 v[154:157], v133 offset:34816
	ds_read_b128 v[158:161], v133 offset:35840
	ds_read_b128 v[186:189], v133 offset:49152
	ds_read_b128 v[190:193], v133 offset:50176
	ds_read_b128 v[194:197], v133 offset:51200
	ds_read_b128 v[198:201], v133 offset:52224
	s_add_u32 s6, vcc_lo, s58
	s_addc_u32 s7, vcc_hi, s59
	s_mov_b32 m0, s91
	ds_read_b128 v[202:205], v184 offset:32768
	ds_read_b128 v[206:209], v184 offset:33792
	ds_read_b128 v[210:213], v184 offset:34816
	ds_read_b128 v[214:217], v184 offset:35840
	ds_read_b128 v[218:221], v184 offset:36864
	ds_read_b128 v[222:225], v184 offset:37888
	ds_read_b128 v[226:229], v184 offset:38912
	ds_read_b128 v[230:233], v184 offset:39936
	global_load_lds_dwordx4 v136, s[6:7]
	s_add_u32 s6, s6, s64
	s_addc_u32 s7, s7, s65
	s_mov_b32 m0, s93
	s_nop 0
	global_load_lds_dwordx4 v136, s[6:7]
	s_waitcnt vmcnt(8)
	s_waitcnt lgkmcnt(0)
	s_barrier
	s_setprio 1
	v_mfma_f32_16x16x32_bf16 v[126:129], v[140:143], v[202:205], v[126:129]
	v_mfma_f32_16x16x32_bf16 v[122:125], v[154:157], v[202:205], v[122:125]
	v_mfma_f32_16x16x32_bf16 v[110:113], v[140:143], v[210:213], v[110:113]
	v_mfma_f32_16x16x32_bf16 v[106:109], v[154:157], v[210:213], v[106:109]
	v_mfma_f32_16x16x32_bf16 v[94:97], v[140:143], v[218:221], v[94:97]
	v_mfma_f32_16x16x32_bf16 v[90:93], v[154:157], v[218:221], v[90:93]
	v_mfma_f32_16x16x32_bf16 v[78:81], v[140:143], v[226:229], v[78:81]
	v_mfma_f32_16x16x32_bf16 v[74:77], v[154:157], v[226:229], v[74:77]
	v_mfma_f32_16x16x32_bf16 v[126:129], v[150:153], v[206:209], v[126:129]
	v_mfma_f32_16x16x32_bf16 v[122:125], v[158:161], v[206:209], v[122:125]
	v_mfma_f32_16x16x32_bf16 v[110:113], v[150:153], v[214:217], v[110:113]
	v_mfma_f32_16x16x32_bf16 v[106:109], v[158:161], v[214:217], v[106:109]
	v_mfma_f32_16x16x32_bf16 v[94:97], v[150:153], v[222:225], v[94:97]
	v_mfma_f32_16x16x32_bf16 v[90:93], v[158:161], v[222:225], v[90:93]
	v_mfma_f32_16x16x32_bf16 v[78:81], v[150:153], v[230:233], v[78:81]
	v_mfma_f32_16x16x32_bf16 v[74:77], v[158:161], v[230:233], v[74:77]
	s_setprio 0
	s_setprio 1
	v_mfma_f32_16x16x32_bf16 v[118:121], v[186:189], v[202:205], v[118:121]
	v_mfma_f32_16x16x32_bf16 v[114:117], v[194:197], v[202:205], v[114:117]
	v_mfma_f32_16x16x32_bf16 v[102:105], v[186:189], v[210:213], v[102:105]
	v_mfma_f32_16x16x32_bf16 v[98:101], v[194:197], v[210:213], v[98:101]
	v_mfma_f32_16x16x32_bf16 v[86:89], v[186:189], v[218:221], v[86:89]
	v_mfma_f32_16x16x32_bf16 v[82:85], v[194:197], v[218:221], v[82:85]
	v_mfma_f32_16x16x32_bf16 v[70:73], v[186:189], v[226:229], v[70:73]
	v_mfma_f32_16x16x32_bf16 v[66:69], v[194:197], v[226:229], v[66:69]
	v_mfma_f32_16x16x32_bf16 v[118:121], v[190:193], v[206:209], v[118:121]
	v_mfma_f32_16x16x32_bf16 v[114:117], v[198:201], v[206:209], v[114:117]
	v_mfma_f32_16x16x32_bf16 v[102:105], v[190:193], v[214:217], v[102:105]
	v_mfma_f32_16x16x32_bf16 v[98:101], v[198:201], v[214:217], v[98:101]
	v_mfma_f32_16x16x32_bf16 v[86:89], v[190:193], v[222:225], v[86:89]
	v_mfma_f32_16x16x32_bf16 v[82:85], v[198:201], v[222:225], v[82:85]
	v_mfma_f32_16x16x32_bf16 v[70:73], v[190:193], v[230:233], v[70:73]
	v_mfma_f32_16x16x32_bf16 v[66:69], v[198:201], v[230:233], v[66:69]
	s_setprio 0
	s_barrier
; #define PG8_STAGE(bufoff, gbase, off, q) do { \
;         __builtin_amdgcn_global_load_lds((const unsigned*)((const char*)(gbase) + (off)), (LAS unsigned*)(lds + (bufoff) + ldsw), 16, 0, 0); \
;         __builtin_amdgcn_global_load_lds((const unsigned*)((const char*)(gbase) + (q) + (off)), (LAS unsigned*)(lds + (bufoff) + ldsw + 8192), 16, 0, 0); } while (0)
; #define PG8_LDA(dst, b, h) do { _Pragma("unroll") for (int m = 0; m < 4; ++m) _Pragma("unroll") for (int k = 0; k < 2; ++k) dst[m][k] = *(const LAS bf16x8*)(lds + PG8_SA(b, h) + aoff + m * 2048 + k * 1024); } while (0)
; #define PG8_MMA(ai, bj, At, Bt) do { __builtin_amdgcn_s_setprio(1); _Pragma("unroll") for (int m = 0; m < 4; ++m) _Pragma("unroll") for (int n = 0; n < 2; ++n) _Pragma("unroll") for (int k = 0; k < 2; ++k) \
;         acc[ai][bj][m][n] = __builtin_amdgcn_mfma_f32_16x16x32_bf16(Bt[n][k], At[m][k], acc[ai][bj][m][n], 0, 0, 0); __builtin_amdgcn_s_setprio(0); } while (0)
; #define PG8_WAIT_V(n) asm volatile("s_waitcnt vmcnt(" #n ")" ::: "memory")
; #define PG8_WAIT_L(n) asm volatile("s_waitcnt lgkmcnt(" #n ")" ::: "memory")
; #define PG8_BAR __builtin_amdgcn_s_barrier()
; #define PG8_SCHED __builtin_amdgcn_sched_barrier(0)
; template <class Epi, class Sched>
; __device__ __forceinline__ void gemm_phase(LAS unsigned char* lds, const int tid, const Sched& S, const Epi& E) {
;     ...
;             PG8_LDA(At, 1, 1); PG8_STAGE(PG8_SB(1, 0), b3, oB2, qB2); PG8_STAGE(PG8_SB(1, 1), b3 + hB2, oB2, qB2); PG8_STAGE(PG8_SA(1, 0), a3, oA2, qA2);
;             PG8_WAIT_V(8); PG8_WAIT_L(0); PG8_BAR; PG8_MMA(1, 0, At, B0); PG8_MMA(1, 1, At, B1); PG8_BAR; PG8_SCHED;
;         }
	s_add_i32 s6, s10, s47
	s_add_i32 m0, s6, 0xffffff80
	ds_read_b128 v[202:205], v184 offset:49152
	ds_read_b128 v[206:209], v184 offset:50176
	ds_read_b128 v[210:213], v184 offset:51200
	ds_read_b128 v[214:217], v184 offset:52224
	ds_read_b128 v[218:221], v184 offset:53248
	ds_read_b128 v[222:225], v184 offset:54272
	ds_read_b128 v[226:229], v184 offset:55296
	ds_read_b128 v[230:233], v184 offset:56320
	global_load_lds_dwordx4 v0, s[28:29] offset:128
	s_add_i32 m0, s6, 0x1f80
	s_add_i32 s6, s11, s47
	s_ashr_i32 s100, s73, 31
	s_add_u32 s98, s28, s73
	s_addc_u32 s99, s29, s100
	global_load_lds_dwordx4 v0, s[98:99] offset:128
	s_add_i32 m0, s6, 0xffffff80
	s_nop 0
	s_ashr_i32 s101, s19, 31
	s_add_u32 s98, s28, s19
	s_addc_u32 s99, s29, s101
	global_load_lds_dwordx4 v0, s[98:99] offset:128
	s_add_i32 m0, s6, 0x1f80
	s_nop 0
	s_add_u32 s98, s98, s73
	s_addc_u32 s99, s99, s100
	global_load_lds_dwordx4 v0, s[98:99] offset:128
	s_add_i32 m0, s77, 0xffffff80
	s_nop 0
	global_load_lds_dwordx4 v136, vcc offset:128
	s_add_i32 m0, s88, 0xffffff80
	s_nop 0
	s_add_u32 s98, vcc_lo, s64
	s_addc_u32 s99, vcc_hi, s65
	global_load_lds_dwordx4 v136, s[98:99] offset:128
	s_waitcnt vmcnt(8)
	s_waitcnt lgkmcnt(0)
	s_barrier
	s_setprio 1
	v_mfma_f32_16x16x32_bf16 v[62:65], v[140:143], v[202:205], v[62:65]
	v_mfma_f32_16x16x32_bf16 v[58:61], v[154:157], v[202:205], v[58:61]
	v_mfma_f32_16x16x32_bf16 v[46:49], v[140:143], v[210:213], v[46:49]
	v_mfma_f32_16x16x32_bf16 v[42:45], v[154:157], v[210:213], v[42:45]
	v_mfma_f32_16x16x32_bf16 v[30:33], v[140:143], v[218:221], v[30:33]
	v_mfma_f32_16x16x32_bf16 v[26:29], v[154:157], v[218:221], v[26:29]
	v_mfma_f32_16x16x32_bf16 v[14:17], v[140:143], v[226:229], v[14:17]
	v_mfma_f32_16x16x32_bf16 v[10:13], v[154:157], v[226:229], v[10:13]
	v_mfma_f32_16x16x32_bf16 v[62:65], v[150:153], v[206:209], v[62:65]
	v_mfma_f32_16x16x32_bf16 v[58:61], v[158:161], v[206:209], v[58:61]
	v_mfma_f32_16x16x32_bf16 v[46:49], v[150:153], v[214:217], v[46:49]
	v_mfma_f32_16x16x32_bf16 v[42:45], v[158:161], v[214:217], v[42:45]
	v_mfma_f32_16x16x32_bf16 v[30:33], v[150:153], v[222:225], v[30:33]
	v_mfma_f32_16x16x32_bf16 v[26:29], v[158:161], v[222:225], v[26:29]
	v_mfma_f32_16x16x32_bf16 v[14:17], v[150:153], v[230:233], v[14:17]
	v_mfma_f32_16x16x32_bf16 v[10:13], v[158:161], v[230:233], v[10:13]
	s_setprio 0
	s_setprio 1
	v_mfma_f32_16x16x32_bf16 v[54:57], v[186:189], v[202:205], v[54:57]
	v_mfma_f32_16x16x32_bf16 v[50:53], v[194:197], v[202:205], v[50:53]
	v_mfma_f32_16x16x32_bf16 v[38:41], v[186:189], v[210:213], v[38:41]
	v_mfma_f32_16x16x32_bf16 v[34:37], v[194:197], v[210:213], v[34:37]
	v_mfma_f32_16x16x32_bf16 v[22:25], v[186:189], v[218:221], v[22:25]
	v_mfma_f32_16x16x32_bf16 v[18:21], v[194:197], v[218:221], v[18:21]
	v_mfma_f32_16x16x32_bf16 v[6:9], v[186:189], v[226:229], v[6:9]
	v_mfma_f32_16x16x32_bf16 v[2:5], v[194:197], v[226:229], v[2:5]
	v_mfma_f32_16x16x32_bf16 v[54:57], v[190:193], v[206:209], v[54:57]
	v_mfma_f32_16x16x32_bf16 v[50:53], v[198:201], v[206:209], v[50:53]
	v_mfma_f32_16x16x32_bf16 v[38:41], v[190:193], v[214:217], v[38:41]
	v_mfma_f32_16x16x32_bf16 v[34:37], v[198:201], v[214:217], v[34:37]
	v_mfma_f32_16x16x32_bf16 v[22:25], v[190:193], v[222:225], v[22:25]
	v_mfma_f32_16x16x32_bf16 v[18:21], v[198:201], v[222:225], v[18:21]
	v_mfma_f32_16x16x32_bf16 v[6:9], v[190:193], v[230:233], v[6:9]
	v_mfma_f32_16x16x32_bf16 v[2:5], v[198:201], v[230:233], v[2:5]
	s_setprio 0
	s_barrier
	s_cmp_ge_i32 s20, s37
	s_cbranch_scc1 .LBB0_177
	s_mov_b32 s17, s20
	s_branch .LBB0_173

; #define PG8_STAGE(bufoff, gbase, off, q) do { \
;         __builtin_amdgcn_global_load_lds((const unsigned*)((const char*)(gbase) + (off)), (LAS unsigned*)(lds + (bufoff) + ldsw), 16, 0, 0); \
;         __builtin_amdgcn_global_load_lds((const unsigned*)((const char*)(gbase) + (q) + (off)), (LAS unsigned*)(lds + (bufoff) + ldsw + 8192), 16, 0, 0); } while (0)
; #define PG8_LDA(dst, b, h) do { _Pragma("unroll") for (int m = 0; m < 4; ++m) _Pragma("unroll") for (int k = 0; k < 2; ++k) dst[m][k] = *(const LAS bf16x8*)(lds + PG8_SA(b, h) + aoff + m * 2048 + k * 1024); } while (0)
; #define PG8_LDB(dst, b, h) do { _Pragma("unroll") for (int n = 0; n < 2; ++n) _Pragma("unroll") for (int k = 0; k < 2; ++k) dst[n][k] = *(const LAS bf16x8*)(lds + PG8_SB(b, h) + boff + n * 2048 + k * 1024); } while (0)
; #define PG8_MMA(ai, bj, At, Bt) do { __builtin_amdgcn_s_setprio(1); _Pragma("unroll") for (int m = 0; m < 4; ++m) _Pragma("unroll") for (int n = 0; n < 2; ++n) _Pragma("unroll") for (int k = 0; k < 2; ++k) \
;         acc[ai][bj][m][n] = __builtin_amdgcn_mfma_f32_16x16x32_bf16(Bt[n][k], At[m][k], acc[ai][bj][m][n], 0, 0, 0); __builtin_amdgcn_s_setprio(0); } while (0)
; template <class Epi, class Sched>
; __device__ __forceinline__ void gemm_phase(LAS unsigned char* lds, const int tid, const Sched& S, const Epi& E) {
;     ...
;             const bool last = (t == nt - 2);
;             const char* a1 = cA + (size_t)(t + 1) * kstep;
;             const char* a2 = last ? nA : cA + (size_t)(t + 2) * kstep; const char* b2 = last ? nB : cB + (size_t)(t + 2) * kstep;
;             const char* a3 = a2 + kstep; const char* b3 = b2 + kstep;
;             const unsigned oA2 = last ? noffA : offA, oB2 = last ? noffB : offB;
;             const int qA2 = last ? nqA : qA, qB2 = last ? nqB : qB, hA2 = last ? nhA : hA, hB2 = last ? nhB : hB;
;             PG8_LDB(B0, 0, 0); PG8_LDB(B1, 0, 1); PG8_SCHED; PG8_LDA(At, 0, 0); PG8_STAGE(PG8_SA(1, 1), a1 + hA, offA, qA);
;             PG8_WAIT_V(8); PG8_WAIT_L(0); PG8_BAR; PG8_MMA(0, 0, At, B0); PG8_MMA(0, 1, At, B1); PG8_BAR; PG8_SCHED;
;             PG8_LDA(At, 0, 1); PG8_STAGE(PG8_SB(0, 0), b2, oB2, qB2); PG8_STAGE(PG8_SB(0, 1), b2 + hB2, oB2, qB2); PG8_STAGE(PG8_SA(0, 0), a2, oA2, qA2);
;             PG8_WAIT_V(8); PG8_WAIT_L(0); PG8_BAR; PG8_MMA(1, 0, At, B0); PG8_MMA(1, 1, At, B1); PG8_BAR; PG8_SCHED;
.Lk0b_175:
	s_or_b32 vcc_lo, s17, 1
	s_mov_b32 vcc_hi, s21
	s_lshl_b64 s[10:11], vcc, 7
	s_add_u32 s17, s40, s6
	s_addc_u32 vcc_lo, s41, s7
	s_and_b64 s[6:7], exec, s[62:63]
	s_cselect_b32 vcc_hi, s82, vcc_lo
	s_cselect_b32 vcc_lo, s48, s17
	s_add_i32 s17, 0, 0x10000
	v_add_u32_e32 v133, s17, v147
	s_add_i32 s62, 0, 0x14000
	ds_read_b128 v[140:143], v133
	ds_read_b128 v[150:153], v133 offset:1024
	ds_read_b128 v[154:157], v133 offset:2048
	ds_read_b128 v[158:161], v133 offset:3072
	ds_read_b128 v[186:189], v133 offset:16384
	ds_read_b128 v[190:193], v133 offset:17408
	ds_read_b128 v[194:197], v133 offset:18432
	ds_read_b128 v[198:201], v133 offset:19456
	s_add_u32 s6, s68, s10
	s_addc_u32 s7, s16, s11
	s_add_i32 m0, s54, 0xc000
	ds_read_b128 v[202:205], v184
	ds_read_b128 v[206:209], v184 offset:1024
	ds_read_b128 v[210:213], v184 offset:2048
	ds_read_b128 v[214:217], v184 offset:3072
	ds_read_b128 v[218:221], v184 offset:4096
	ds_read_b128 v[222:225], v184 offset:5120
	ds_read_b128 v[226:229], v184 offset:6144
	ds_read_b128 v[230:233], v184 offset:7168
	global_load_lds_dwordx4 v134, s[6:7]
	s_add_u32 s6, s6, s66
	s_addc_u32 s7, s7, s67
	s_add_i32 m0, s54, 0xe000
	s_nop 0
	global_load_lds_dwordx4 v134, s[6:7]
	s_waitcnt vmcnt(24)
	s_waitcnt lgkmcnt(0)
	s_barrier
	s_setprio 1
	v_mfma_f32_16x16x32_bf16 v[126:129], v[140:143], v[202:205], v[126:129]
	v_mfma_f32_16x16x32_bf16 v[122:125], v[154:157], v[202:205], v[122:125]
	v_mfma_f32_16x16x32_bf16 v[110:113], v[140:143], v[210:213], v[110:113]
	v_mfma_f32_16x16x32_bf16 v[106:109], v[154:157], v[210:213], v[106:109]
	v_mfma_f32_16x16x32_bf16 v[94:97], v[140:143], v[218:221], v[94:97]
	v_mfma_f32_16x16x32_bf16 v[90:93], v[154:157], v[218:221], v[90:93]
	v_mfma_f32_16x16x32_bf16 v[78:81], v[140:143], v[226:229], v[78:81]
	v_mfma_f32_16x16x32_bf16 v[74:77], v[154:157], v[226:229], v[74:77]
	v_mfma_f32_16x16x32_bf16 v[126:129], v[150:153], v[206:209], v[126:129]
	v_mfma_f32_16x16x32_bf16 v[122:125], v[158:161], v[206:209], v[122:125]
	v_mfma_f32_16x16x32_bf16 v[110:113], v[150:153], v[214:217], v[110:113]
	v_mfma_f32_16x16x32_bf16 v[106:109], v[158:161], v[214:217], v[106:109]
	v_mfma_f32_16x16x32_bf16 v[94:97], v[150:153], v[222:225], v[94:97]
	v_mfma_f32_16x16x32_bf16 v[90:93], v[158:161], v[222:225], v[90:93]
	v_mfma_f32_16x16x32_bf16 v[78:81], v[150:153], v[230:233], v[78:81]
	v_mfma_f32_16x16x32_bf16 v[74:77], v[158:161], v[230:233], v[74:77]
	s_setprio 0
	s_setprio 1
	v_mfma_f32_16x16x32_bf16 v[118:121], v[186:189], v[202:205], v[118:121]
	v_mfma_f32_16x16x32_bf16 v[114:117], v[194:197], v[202:205], v[114:117]
	v_mfma_f32_16x16x32_bf16 v[102:105], v[186:189], v[210:213], v[102:105]
	v_mfma_f32_16x16x32_bf16 v[98:101], v[194:197], v[210:213], v[98:101]
	v_mfma_f32_16x16x32_bf16 v[86:89], v[186:189], v[218:221], v[86:89]
	v_mfma_f32_16x16x32_bf16 v[82:85], v[194:197], v[218:221], v[82:85]
	v_mfma_f32_16x16x32_bf16 v[70:73], v[186:189], v[226:229], v[70:73]
	v_mfma_f32_16x16x32_bf16 v[66:69], v[194:197], v[226:229], v[66:69]
	v_mfma_f32_16x16x32_bf16 v[118:121], v[190:193], v[206:209], v[118:121]
	v_mfma_f32_16x16x32_bf16 v[114:117], v[198:201], v[206:209], v[114:117]
	v_mfma_f32_16x16x32_bf16 v[102:105], v[190:193], v[214:217], v[102:105]
	v_mfma_f32_16x16x32_bf16 v[98:101], v[198:201], v[214:217], v[98:101]
	v_mfma_f32_16x16x32_bf16 v[86:89], v[190:193], v[222:225], v[86:89]
	v_mfma_f32_16x16x32_bf16 v[82:85], v[198:201], v[222:225], v[82:85]
	v_mfma_f32_16x16x32_bf16 v[70:73], v[190:193], v[230:233], v[70:73]
	v_mfma_f32_16x16x32_bf16 v[66:69], v[198:201], v[230:233], v[66:69]
	s_setprio 0
	s_barrier
	s_add_i32 s10, s17, s47
	s_ashr_i32 s11, s73, 31
	s_mov_b32 m0, s10
	s_add_u32 s6, s28, s73
	ds_read_b128 v[202:205], v184 offset:16384
	ds_read_b128 v[206:209], v184 offset:17408
	ds_read_b128 v[210:213], v184 offset:18432
	ds_read_b128 v[214:217], v184 offset:19456
	ds_read_b128 v[218:221], v184 offset:20480
	ds_read_b128 v[222:225], v184 offset:21504
	ds_read_b128 v[226:229], v184 offset:22528
	ds_read_b128 v[230:233], v184 offset:23552
	global_load_lds_dwordx4 v0, s[28:29]
	s_addc_u32 s7, s29, s11
	s_add_i32 m0, s10, 0x2000
	s_nop 0
	global_load_lds_dwordx4 v0, s[6:7]
	s_ashr_i32 s7, s19, 31
	s_add_u32 s6, s28, s19
	s_addc_u32 s7, s29, s7
	s_add_i32 s10, s62, s47
	s_mov_b32 m0, s10
	s_nop 0
	global_load_lds_dwordx4 v0, s[6:7]
	s_add_u32 s6, s6, s73
	s_addc_u32 s7, s7, s11
	s_add_i32 m0, s10, 0x2000
	s_nop 0
	global_load_lds_dwordx4 v0, s[6:7]
	s_add_u32 s6, vcc_lo, s64
	s_mov_b32 m0, s54
	s_addc_u32 s7, vcc_hi, s65
	global_load_lds_dwordx4 v136, vcc
	s_mov_b32 m0, s55
	s_nop 0
	global_load_lds_dwordx4 v136, s[6:7]
	s_waitcnt vmcnt(24)
	s_waitcnt lgkmcnt(0)
	s_barrier
; #define PG8_STAGE(bufoff, gbase, off, q) do { \
;         __builtin_amdgcn_global_load_lds((const unsigned*)((const char*)(gbase) + (off)), (LAS unsigned*)(lds + (bufoff) + ldsw), 16, 0, 0); \
;         __builtin_amdgcn_global_load_lds((const unsigned*)((const char*)(gbase) + (q) + (off)), (LAS unsigned*)(lds + (bufoff) + ldsw + 8192), 16, 0, 0); } while (0)
; #define PG8_LDA(dst, b, h) do { _Pragma("unroll") for (int m = 0; m < 4; ++m) _Pragma("unroll") for (int k = 0; k < 2; ++k) dst[m][k] = *(const LAS bf16x8*)(lds + PG8_SA(b, h) + aoff + m * 2048 + k * 1024); } while (0)
; #define PG8_LDB(dst, b, h) do { _Pragma("unroll") for (int n = 0; n < 2; ++n) _Pragma("unroll") for (int k = 0; k < 2; ++k) dst[n][k] = *(const LAS bf16x8*)(lds + PG8_SB(b, h) + boff + n * 2048 + k * 1024); } while (0)
; #define PG8_MMA(ai, bj, At, Bt) do { __builtin_amdgcn_s_setprio(1); _Pragma("unroll") for (int m = 0; m < 4; ++m) _Pragma("unroll") for (int n = 0; n < 2; ++n) _Pragma("unroll") for (int k = 0; k < 2; ++k) \
;         acc[ai][bj][m][n] = __builtin_amdgcn_mfma_f32_16x16x32_bf16(Bt[n][k], At[m][k], acc[ai][bj][m][n], 0, 0, 0); __builtin_amdgcn_s_setprio(0); } while (0)
; #define PG8_WAIT_V(n) asm volatile("s_waitcnt vmcnt(" #n ")" ::: "memory")
; #define PG8_WAIT_L(n) asm volatile("s_waitcnt lgkmcnt(" #n ")" ::: "memory")
; #define PG8_BAR __builtin_amdgcn_s_barrier()
; #define PG8_SCHED __builtin_amdgcn_sched_barrier(0)
; template <class Epi, class Sched>
; __device__ __forceinline__ void gemm_phase(LAS unsigned char* lds, const int tid, const Sched& S, const Epi& E) {
;     ...
;             PG8_WAIT_V(8); PG8_WAIT_L(0); PG8_BAR; PG8_MMA(1, 0, At, B0); PG8_MMA(1, 1, At, B1); PG8_BAR; PG8_SCHED;
;             PG8_LDB(B0, 1, 0); PG8_LDB(B1, 1, 1); PG8_SCHED; PG8_LDA(At, 1, 0); PG8_STAGE(PG8_SA(0, 1), a2 + hA2, oA2, qA2);
;             PG8_WAIT_V(8); PG8_WAIT_L(0); PG8_BAR; PG8_MMA(0, 0, At, B0); PG8_MMA(0, 1, At, B1); PG8_BAR; PG8_SCHED;
	s_setprio 1
	v_mfma_f32_16x16x32_bf16 v[62:65], v[140:143], v[202:205], v[62:65]
	v_mfma_f32_16x16x32_bf16 v[58:61], v[154:157], v[202:205], v[58:61]
	v_mfma_f32_16x16x32_bf16 v[46:49], v[140:143], v[210:213], v[46:49]
	v_mfma_f32_16x16x32_bf16 v[42:45], v[154:157], v[210:213], v[42:45]
	v_mfma_f32_16x16x32_bf16 v[30:33], v[140:143], v[218:221], v[30:33]
	v_mfma_f32_16x16x32_bf16 v[26:29], v[154:157], v[218:221], v[26:29]
	v_mfma_f32_16x16x32_bf16 v[14:17], v[140:143], v[226:229], v[14:17]
	v_mfma_f32_16x16x32_bf16 v[10:13], v[154:157], v[226:229], v[10:13]
	v_mfma_f32_16x16x32_bf16 v[62:65], v[150:153], v[206:209], v[62:65]
	v_mfma_f32_16x16x32_bf16 v[58:61], v[158:161], v[206:209], v[58:61]
	v_mfma_f32_16x16x32_bf16 v[46:49], v[150:153], v[214:217], v[46:49]
	v_mfma_f32_16x16x32_bf16 v[42:45], v[158:161], v[214:217], v[42:45]
	v_mfma_f32_16x16x32_bf16 v[30:33], v[150:153], v[222:225], v[30:33]
	v_mfma_f32_16x16x32_bf16 v[26:29], v[158:161], v[222:225], v[26:29]
	v_mfma_f32_16x16x32_bf16 v[14:17], v[150:153], v[230:233], v[14:17]
	v_mfma_f32_16x16x32_bf16 v[10:13], v[158:161], v[230:233], v[10:13]
	s_setprio 0
	s_setprio 1
	v_mfma_f32_16x16x32_bf16 v[54:57], v[186:189], v[202:205], v[54:57]
	v_mfma_f32_16x16x32_bf16 v[50:53], v[194:197], v[202:205], v[50:53]
	v_mfma_f32_16x16x32_bf16 v[38:41], v[186:189], v[210:213], v[38:41]
	v_mfma_f32_16x16x32_bf16 v[34:37], v[194:197], v[210:213], v[34:37]
	v_mfma_f32_16x16x32_bf16 v[22:25], v[186:189], v[218:221], v[22:25]
	v_mfma_f32_16x16x32_bf16 v[18:21], v[194:197], v[218:221], v[18:21]
	v_mfma_f32_16x16x32_bf16 v[6:9], v[186:189], v[226:229], v[6:9]
	v_mfma_f32_16x16x32_bf16 v[2:5], v[194:197], v[226:229], v[2:5]
	v_mfma_f32_16x16x32_bf16 v[54:57], v[190:193], v[206:209], v[54:57]
	v_mfma_f32_16x16x32_bf16 v[50:53], v[198:201], v[206:209], v[50:53]
	v_mfma_f32_16x16x32_bf16 v[38:41], v[190:193], v[214:217], v[38:41]
	v_mfma_f32_16x16x32_bf16 v[34:37], v[198:201], v[214:217], v[34:37]
	v_mfma_f32_16x16x32_bf16 v[22:25], v[190:193], v[222:225], v[22:25]
	v_mfma_f32_16x16x32_bf16 v[18:21], v[198:201], v[222:225], v[18:21]
	v_mfma_f32_16x16x32_bf16 v[6:9], v[190:193], v[230:233], v[6:9]
	v_mfma_f32_16x16x32_bf16 v[2:5], v[198:201], v[230:233], v[2:5]
	s_setprio 0
	s_barrier
	s_add_i32 s10, 0, 0x18000
	s_add_i32 s11, 0, 0x1c000
	ds_read_b128 v[140:143], v133 offset:32768
	ds_read_b128 v[150:153], v133 offset:33792
	ds_read_b128 v[154:157], v133 offset:34816
	ds_read_b128 v[158:161], v133 offset:35840
	ds_read_b128 v[186:189], v133 offset:49152
	ds_read_b128 v[190:193], v133 offset:50176
	ds_read_b128 v[194:197], v133 offset:51200
	ds_read_b128 v[198:201], v133 offset:52224
	s_add_u32 s6, vcc_lo, s58
	s_addc_u32 s7, vcc_hi, s59
	s_mov_b32 m0, s91
	ds_read_b128 v[202:205], v184 offset:32768
	ds_read_b128 v[206:209], v184 offset:33792
	ds_read_b128 v[210:213], v184 offset:34816
	ds_read_b128 v[214:217], v184 offset:35840
	ds_read_b128 v[218:221], v184 offset:36864
	ds_read_b128 v[222:225], v184 offset:37888
	ds_read_b128 v[226:229], v184 offset:38912
	ds_read_b128 v[230:233], v184 offset:39936
	global_load_lds_dwordx4 v136, s[6:7]
	s_add_u32 s6, s6, s64
	s_addc_u32 s7, s7, s65
	s_mov_b32 m0, s93
	s_nop 0
	global_load_lds_dwordx4 v136, s[6:7]
	s_waitcnt vmcnt(8)
	s_waitcnt lgkmcnt(0)
	s_barrier
	s_setprio 1
	v_mfma_f32_16x16x32_bf16 v[126:129], v[140:143], v[202:205], v[126:129]
	v_mfma_f32_16x16x32_bf16 v[122:125], v[154:157], v[202:205], v[122:125]
	v_mfma_f32_16x16x32_bf16 v[110:113], v[140:143], v[210:213], v[110:113]
	v_mfma_f32_16x16x32_bf16 v[106:109], v[154:157], v[210:213], v[106:109]
	v_mfma_f32_16x16x32_bf16 v[94:97], v[140:143], v[218:221], v[94:97]
	v_mfma_f32_16x16x32_bf16 v[90:93], v[154:157], v[218:221], v[90:93]
	v_mfma_f32_16x16x32_bf16 v[78:81], v[140:143], v[226:229], v[78:81]
	v_mfma_f32_16x16x32_bf16 v[74:77], v[154:157], v[226:229], v[74:77]
	v_mfma_f32_16x16x32_bf16 v[126:129], v[150:153], v[206:209], v[126:129]
	v_mfma_f32_16x16x32_bf16 v[122:125], v[158:161], v[206:209], v[122:125]
	v_mfma_f32_16x16x32_bf16 v[110:113], v[150:153], v[214:217], v[110:113]
	v_mfma_f32_16x16x32_bf16 v[106:109], v[158:161], v[214:217], v[106:109]
	v_mfma_f32_16x16x32_bf16 v[94:97], v[150:153], v[222:225], v[94:97]
	v_mfma_f32_16x16x32_bf16 v[90:93], v[158:161], v[222:225], v[90:93]
	v_mfma_f32_16x16x32_bf16 v[78:81], v[150:153], v[230:233], v[78:81]
	v_mfma_f32_16x16x32_bf16 v[74:77], v[158:161], v[230:233], v[74:77]
	s_setprio 0
	s_setprio 1
	v_mfma_f32_16x16x32_bf16 v[118:121], v[186:189], v[202:205], v[118:121]
	v_mfma_f32_16x16x32_bf16 v[114:117], v[194:197], v[202:205], v[114:117]
	v_mfma_f32_16x16x32_bf16 v[102:105], v[186:189], v[210:213], v[102:105]
	v_mfma_f32_16x16x32_bf16 v[98:101], v[194:197], v[210:213], v[98:101]
	v_mfma_f32_16x16x32_bf16 v[86:89], v[186:189], v[218:221], v[86:89]
	v_mfma_f32_16x16x32_bf16 v[82:85], v[194:197], v[218:221], v[82:85]
	v_mfma_f32_16x16x32_bf16 v[70:73], v[186:189], v[226:229], v[70:73]
	v_mfma_f32_16x16x32_bf16 v[66:69], v[194:197], v[226:229], v[66:69]
	v_mfma_f32_16x16x32_bf16 v[118:121], v[190:193], v[206:209], v[118:121]
	v_mfma_f32_16x16x32_bf16 v[114:117], v[198:201], v[206:209], v[114:117]
	v_mfma_f32_16x16x32_bf16 v[102:105], v[190:193], v[214:217], v[102:105]
	v_mfma_f32_16x16x32_bf16 v[98:101], v[198:201], v[214:217], v[98:101]
	v_mfma_f32_16x16x32_bf16 v[86:89], v[190:193], v[222:225], v[86:89]
	v_mfma_f32_16x16x32_bf16 v[82:85], v[198:201], v[222:225], v[82:85]
	v_mfma_f32_16x16x32_bf16 v[70:73], v[190:193], v[230:233], v[70:73]
	v_mfma_f32_16x16x32_bf16 v[66:69], v[198:201], v[230:233], v[66:69]
	s_setprio 0
	s_barrier
; #define PG8_STAGE(bufoff, gbase, off, q) do { \
;         __builtin_amdgcn_global_load_lds((const unsigned*)((const char*)(gbase) + (off)), (LAS unsigned*)(lds + (bufoff) + ldsw), 16, 0, 0); \
;         __builtin_amdgcn_global_load_lds((const unsigned*)((const char*)(gbase) + (q) + (off)), (LAS unsigned*)(lds + (bufoff) + ldsw + 8192), 16, 0, 0); } while (0)
; #define PG8_LDA(dst, b, h) do { _Pragma("unroll") for (int m = 0; m < 4; ++m) _Pragma("unroll") for (int k = 0; k < 2; ++k) dst[m][k] = *(const LAS bf16x8*)(lds + PG8_SA(b, h) + aoff + m * 2048 + k * 1024); } while (0)
; #define PG8_MMA(ai, bj, At, Bt) do { __builtin_amdgcn_s_setprio(1); _Pragma("unroll") for (int m = 0; m < 4; ++m) _Pragma("unroll") for (int n = 0; n < 2; ++n) _Pragma("unroll") for (int k = 0; k < 2; ++k) \
;         acc[ai][bj][m][n] = __builtin_amdgcn_mfma_f32_16x16x32_bf16(Bt[n][k], At[m][k], acc[ai][bj][m][n], 0, 0, 0); __builtin_amdgcn_s_setprio(0); } while (0)
; #define PG8_WAIT_V(n) asm volatile("s_waitcnt vmcnt(" #n ")" ::: "memory")
; #define PG8_WAIT_L(n) asm volatile("s_waitcnt lgkmcnt(" #n ")" ::: "memory")
; #define PG8_BAR __builtin_amdgcn_s_barrier()
; #define PG8_SCHED __builtin_amdgcn_sched_barrier(0)
; template <class Epi, class Sched>
; __device__ __forceinline__ void gemm_phase(LAS unsigned char* lds, const int tid, const Sched& S, const Epi& E) {
;     ...
;             PG8_LDA(At, 1, 1); PG8_STAGE(PG8_SB(1, 0), b3, oB2, qB2); PG8_STAGE(PG8_SB(1, 1), b3 + hB2, oB2, qB2); PG8_STAGE(PG8_SA(1, 0), a3, oA2, qA2);
;             PG8_WAIT_V(8); PG8_WAIT_L(0); PG8_BAR; PG8_MMA(1, 0, At, B0); PG8_MMA(1, 1, At, B1); PG8_BAR; PG8_SCHED;
;         }
	s_add_i32 s6, s10, s47
	s_add_i32 m0, s6, 0xffffff80
	ds_read_b128 v[202:205], v184 offset:49152
	ds_read_b128 v[206:209], v184 offset:50176
	ds_read_b128 v[210:213], v184 offset:51200
	ds_read_b128 v[214:217], v184 offset:52224
	ds_read_b128 v[218:221], v184 offset:53248
	ds_read_b128 v[222:225], v184 offset:54272
	ds_read_b128 v[226:229], v184 offset:55296
	ds_read_b128 v[230:233], v184 offset:56320
	global_load_lds_dwordx4 v0, s[28:29] offset:128
	s_add_i32 m0, s6, 0x1f80
	s_add_i32 s6, s11, s47
	s_ashr_i32 s100, s73, 31
	s_add_u32 s98, s28, s73
	s_addc_u32 s99, s29, s100
	global_load_lds_dwordx4 v0, s[98:99] offset:128
	s_add_i32 m0, s6, 0xffffff80
	s_nop 0
	s_ashr_i32 s101, s19, 31
	s_add_u32 s98, s28, s19
	s_addc_u32 s99, s29, s101
	global_load_lds_dwordx4 v0, s[98:99] offset:128
	s_add_i32 m0, s6, 0x1f80
	s_nop 0
	s_add_u32 s98, s98, s73
	s_addc_u32 s99, s99, s100
	global_load_lds_dwordx4 v0, s[98:99] offset:128
	s_add_i32 m0, s77, 0xffffff80
	s_nop 0
	global_load_lds_dwordx4 v136, vcc offset:128
	s_add_i32 m0, s88, 0xffffff80
	s_nop 0
	s_add_u32 s98, vcc_lo, s64
	s_addc_u32 s99, vcc_hi, s65
	global_load_lds_dwordx4 v136, s[98:99] offset:128
	s_waitcnt vmcnt(8)
	s_waitcnt lgkmcnt(0)
	s_barrier
	s_setprio 1
	v_mfma_f32_16x16x32_bf16 v[62:65], v[140:143], v[202:205], v[62:65]
	v_mfma_f32_16x16x32_bf16 v[58:61], v[154:157], v[202:205], v[58:61]
	v_mfma_f32_16x16x32_bf16 v[46:49], v[140:143], v[210:213], v[46:49]
	v_mfma_f32_16x16x32_bf16 v[42:45], v[154:157], v[210:213], v[42:45]
	v_mfma_f32_16x16x32_bf16 v[30:33], v[140:143], v[218:221], v[30:33]
	v_mfma_f32_16x16x32_bf16 v[26:29], v[154:157], v[218:221], v[26:29]
	v_mfma_f32_16x16x32_bf16 v[14:17], v[140:143], v[226:229], v[14:17]
	v_mfma_f32_16x16x32_bf16 v[10:13], v[154:157], v[226:229], v[10:13]
	v_mfma_f32_16x16x32_bf16 v[62:65], v[150:153], v[206:209], v[62:65]
	v_mfma_f32_16x16x32_bf16 v[58:61], v[158:161], v[206:209], v[58:61]
	v_mfma_f32_16x16x32_bf16 v[46:49], v[150:153], v[214:217], v[46:49]
	v_mfma_f32_16x16x32_bf16 v[42:45], v[158:161], v[214:217], v[42:45]
	v_mfma_f32_16x16x32_bf16 v[30:33], v[150:153], v[222:225], v[30:33]
	v_mfma_f32_16x16x32_bf16 v[26:29], v[158:161], v[222:225], v[26:29]
	v_mfma_f32_16x16x32_bf16 v[14:17], v[150:153], v[230:233], v[14:17]
	v_mfma_f32_16x16x32_bf16 v[10:13], v[158:161], v[230:233], v[10:13]
	s_setprio 0
	s_setprio 1
	v_mfma_f32_16x16x32_bf16 v[54:57], v[186:189], v[202:205], v[54:57]
	v_mfma_f32_16x16x32_bf16 v[50:53], v[194:197], v[202:205], v[50:53]
	v_mfma_f32_16x16x32_bf16 v[38:41], v[186:189], v[210:213], v[38:41]
	v_mfma_f32_16x16x32_bf16 v[34:37], v[194:197], v[210:213], v[34:37]
	v_mfma_f32_16x16x32_bf16 v[22:25], v[186:189], v[218:221], v[22:25]
	v_mfma_f32_16x16x32_bf16 v[18:21], v[194:197], v[218:221], v[18:21]
	v_mfma_f32_16x16x32_bf16 v[6:9], v[186:189], v[226:229], v[6:9]
	v_mfma_f32_16x16x32_bf16 v[2:5], v[194:197], v[226:229], v[2:5]
	v_mfma_f32_16x16x32_bf16 v[54:57], v[190:193], v[206:209], v[54:57]
	v_mfma_f32_16x16x32_bf16 v[50:53], v[198:201], v[206:209], v[50:53]
	v_mfma_f32_16x16x32_bf16 v[38:41], v[190:193], v[214:217], v[38:41]
	v_mfma_f32_16x16x32_bf16 v[34:37], v[198:201], v[214:217], v[34:37]
	v_mfma_f32_16x16x32_bf16 v[22:25], v[190:193], v[222:225], v[22:25]
	v_mfma_f32_16x16x32_bf16 v[18:21], v[198:201], v[222:225], v[18:21]
	v_mfma_f32_16x16x32_bf16 v[6:9], v[190:193], v[230:233], v[6:9]
	v_mfma_f32_16x16x32_bf16 v[2:5], v[198:201], v[230:233], v[2:5]
	s_setprio 0
	s_barrier
	s_cmp_ge_i32 s20, s37
	s_cbranch_scc1 .LBB0_177
	s_mov_b32 s17, s20
	s_branch .LBB0_173
